# GEMM1 epilogue: per-row rstd values fetched at the top of the tile (before the K-loop) into spare VGPRs; epilogue no longer begins with a load round trip + vmcnt(0)
# baseline (speedup 1.0000x reference)
;     __host__ __device__ bool next(int i, Unit& u) const {
;         const long L = (long)i * G + c; if (L >= nwg) return false;
;         int wgid = (int)L; { const int q = nwg / NXCD, r = nwg % NXCD, xcd = wgid % NXCD, off = wgid / NXCD; wgid = (xcd < r ? xcd * (q + 1) : r * (q + 1) + (xcd - r) * q) + off; }
;         const int nig = WGM * nN, gid = wgid / nig, fm = gid * WGM, gsz = (nM - fm) < WGM ? (nM - fm) : WGM;
;         u.pm = fm + ((wgid % nig) % gsz); u.pn = (wgid % nig) / gsz; return true;
;     __device__ __forceinline__ void operator()(const f32x4 (&acc)[2][2][4][2], const pg8::Unit& u, int wr, int wc, int fr, int fq) const {
;     ...
;         for (int i = 0; i < 8; ++i) rs[i] = rstd[row0 + (i >> 2) * 128 + (i & 3) * 16];
.LBB0_83:
	v_lshl_add_u32 v236, s49, 8, v143
	v_ashrrev_i32_e32 v237, 31, v236
	v_lshl_add_u64 v[236:237], v[236:237], 2, s[14:15]
	global_load_dword v243, v[236:237], off
	global_load_dword v244, v[236:237], off offset:64
	global_load_dword v245, v[236:237], off offset:128
	global_load_dword v246, v[236:237], off offset:192
	global_load_dword v247, v[236:237], off offset:512
	global_load_dword v248, v[236:237], off offset:576
	global_load_dword v249, v[236:237], off offset:640
	global_load_dword v250, v[236:237], off offset:704
	s_add_i32 s47, s47, 1
	s_mul_i32 s19, s47, s46
	s_mul_hi_u32 s26, s47, s9
	s_add_i32 s19, s26, s19
	s_mul_i32 s26, s47, s9
	s_add_u32 s26, s26, s2
	s_addc_u32 s27, s19, s3
	v_mov_b64_e32 v[4:5], 0xa00
	v_cmp_lt_i64_e64 s[36:37], s[26:27], v[4:5]
	v_mov_b64_e32 v[4:5], 0x9ff
	v_cmp_gt_i64_e32 vcc, s[26:27], v[4:5]
	s_cbranch_vccnz .LBB0_85
	s_ashr_i32 s18, s26, 31
	s_lshr_b32 s18, s18, 29
	s_add_i32 s18, s26, s18
	s_ashr_i32 s19, s18, 3
	s_and_b32 s18, s18, -8
	s_sub_i32 s18, s26, s18
	s_cmp_lt_i32 s18, 0
	s_cselect_b32 s26, s85, 0x140
	s_mul_i32 s18, s26, s18
	s_add_i32 s18, s18, s19
	s_mul_hi_i32 s19, s18, 0x66666667
	s_lshr_b32 s26, s19, 31
	s_ashr_i32 s19, s19, 8
	s_add_i32 s19, s19, s26
	s_lshl_b32 s26, s19, 3
	s_sub_i32 s27, 32, s26
	s_min_i32 s27, s27, 8
	s_abs_i32 s28, s27
	v_cvt_f32_u32_e32 v4, s28
	s_sub_i32 s30, 0, s28
	s_mulk_i32 s19, 0x280
	s_sub_i32 s19, s18, s19
	v_rcp_iflag_f32_e32 v4, v4
	s_abs_i32 s18, s19
	s_xor_b32 s29, s19, s27
	s_ashr_i32 s29, s29, 31
	v_mul_f32_e32 v4, 0x4f7ffffe, v4
	v_cvt_u32_f32_e32 v4, v4
	s_nop 0
	v_readfirstlane_b32 s31, v4
	s_mul_i32 s30, s30, s31
	s_mul_hi_u32 s30, s31, s30
	s_add_i32 s31, s31, s30
	s_mul_hi_u32 s30, s18, s31
	s_mul_i32 s31, s30, s28
	s_sub_i32 s18, s18, s31
	s_add_i32 s34, s30, 1
	s_sub_i32 s31, s18, s28
	s_cmp_ge_u32 s18, s28
	s_cselect_b32 s30, s34, s30
	s_cselect_b32 s18, s31, s18
	s_add_i32 s31, s30, 1
	s_cmp_ge_u32 s18, s28
	s_cselect_b32 s18, s31, s30
	s_xor_b32 s18, s18, s29
	s_sub_i32 s18, s18, s29
	s_mul_i32 s27, s18, s27
	s_sub_i32 s19, s19, s27
	s_add_i32 s28, s19, s26

; __device__ __forceinline__ unsigned cvt_pk_bf16(float lo, float hi) { unsigned r; asm volatile("v_cvt_pk_bf16_f32 %0, %1, %2" : "=v"(r) : "v"(lo), "v"(hi)); return r; }
; #define GAS __attribute__((address_space(1)))
;     __device__ __forceinline__ void operator()(const f32x4 (&acc)[2][2][4][2], const pg8::Unit& u, int wr, int wc, int fr, int fq) const {
;         const int row0 = u.pm * 256 + wr * 64 + fr, col0 = u.pn * 256 + wc * 32 + 8 * fq;
;         float rs[8];
; #pragma unroll
;         for (int i = 0; i < 8; ++i) rs[i] = rstd[row0 + (i >> 2) * 128 + (i & 3) * 16];
; #pragma unroll
;         for (int ai = 0; ai < 2; ++ai)
; #pragma unroll
;             for (int m = 0; m < 4; ++m) { const int row = row0 + ai * 128 + m * 16; const float r = rs[ai * 4 + m]; GAS bf16* rowp = O + (size_t)row * NPROJ + col0;
; #pragma unroll
;                 for (int bj = 0; bj < 2; ++bj) { const f32x4 v0 = acc[ai][bj][m][0] * r, v1 = acc[ai][bj][m][1] * r; v4u w;
;                     w.x = cvt_pk_bf16(v0[0], v0[1]); w.y = cvt_pk_bf16(v0[2], v0[3]); w.z = cvt_pk_bf16(v1[0], v1[1]); w.w = cvt_pk_bf16(v1[2], v1[3]);
;                     *(GAS v4u*)(rowp + bj * 128) = w; } }
.LBB0_89:
	v_lshl_add_u32 v144, s49, 8, v143
	v_ashrrev_i32_e32 v145, 31, v144
	v_lshl_add_u64 v[148:149], v[144:145], 2, s[14:15]
	v_mov_b32_e32 v160, v243
	v_mov_b32_e32 v162, v244
	v_mov_b32_e32 v158, v245
	v_mov_b32_e32 v156, v246
	v_mov_b32_e32 v154, v247
	v_mov_b32_e32 v152, v248
	v_mov_b32_e32 v146, v249
	v_mov_b32_e32 v142, v250
	v_lshl_or_b32 v150, s48, 8, v153
	v_ashrrev_i32_e32 v151, 31, v150
	v_mov_b64_e32 v[148:149], s[12:13]
	v_mad_i64_i32 v[164:165], s[26:27], v144, s4, v[148:149]
	v_lshlrev_b64 v[150:151], 1, v[150:151]
	v_lshl_add_u64 v[164:165], v[164:165], 0, v[150:151]
	v_add_u32_e32 v145, 0x80, v144
	s_andn2_b64 vcc, exec, s[36:37]
	v_pk_mul_f32 v[130:131], v[130:131], v[160:161] op_sel_hi:[1,0]
	v_pk_mul_f32 v[128:129], v[128:129], v[160:161] op_sel_hi:[1,0]
	v_pk_mul_f32 v[166:167], v[126:127], v[160:161] op_sel_hi:[1,0]
	v_pk_mul_f32 v[126:127], v[124:125], v[160:161] op_sel_hi:[1,0]
	v_cvt_pk_bf16_f32 v124, v128, v129
	v_cvt_pk_bf16_f32 v125, v130, v131
	v_pk_mul_f32 v[120:121], v[120:121], v[160:161] op_sel_hi:[1,0]
	v_cvt_pk_bf16_f32 v126, v126, v127
	v_cvt_pk_bf16_f32 v127, v166, v167
	global_store_dwordx4 v[164:165], v[124:127], off
	v_pk_mul_f32 v[122:123], v[122:123], v[160:161] op_sel_hi:[1,0]
	v_pk_mul_f32 v[114:115], v[114:115], v[162:163] op_sel_hi:[1,0]
	v_pk_mul_f32 v[124:125], v[118:119], v[160:161] op_sel_hi:[1,0]
	v_pk_mul_f32 v[118:119], v[116:117], v[160:161] op_sel_hi:[1,0]
	v_cvt_pk_bf16_f32 v116, v120, v121
	v_cvt_pk_bf16_f32 v117, v122, v123
	v_pk_mul_f32 v[112:113], v[112:113], v[162:163] op_sel_hi:[1,0]
	v_cvt_pk_bf16_f32 v118, v118, v119
	v_cvt_pk_bf16_f32 v119, v124, v125
	global_store_dwordx4 v[164:165], v[116:119], off offset:256
	v_pk_mul_f32 v[104:105], v[104:105], v[162:163] op_sel_hi:[1,0]
	v_pk_mul_f32 v[106:107], v[106:107], v[162:163] op_sel_hi:[1,0]
	v_or_b32_e32 v116, 16, v144
	v_mad_i64_i32 v[116:117], s[26:27], v116, s4, v[148:149]
	v_lshl_add_u64 v[116:117], v[116:117], 0, v[150:151]
	v_pk_mul_f32 v[118:119], v[110:111], v[162:163] op_sel_hi:[1,0]
	v_pk_mul_f32 v[110:111], v[108:109], v[162:163] op_sel_hi:[1,0]
	v_cvt_pk_bf16_f32 v108, v112, v113
	v_cvt_pk_bf16_f32 v109, v114, v115
	v_pk_mul_f32 v[98:99], v[98:99], v[158:159] op_sel_hi:[1,0]
	v_cvt_pk_bf16_f32 v110, v110, v111
	v_cvt_pk_bf16_f32 v111, v118, v119
	global_store_dwordx4 v[116:117], v[108:111], off
	v_pk_mul_f32 v[96:97], v[96:97], v[158:159] op_sel_hi:[1,0]
	v_pk_mul_f32 v[88:89], v[88:89], v[158:159] op_sel_hi:[1,0]
	v_pk_mul_f32 v[108:109], v[102:103], v[162:163] op_sel_hi:[1,0]
	v_pk_mul_f32 v[102:103], v[100:101], v[162:163] op_sel_hi:[1,0]
	v_cvt_pk_bf16_f32 v100, v104, v105
	v_cvt_pk_bf16_f32 v101, v106, v107
	v_pk_mul_f32 v[90:91], v[90:91], v[158:159] op_sel_hi:[1,0]
	v_cvt_pk_bf16_f32 v102, v102, v103
	v_cvt_pk_bf16_f32 v103, v108, v109
	global_store_dwordx4 v[116:117], v[100:103], off offset:256
	v_pk_mul_f32 v[82:83], v[82:83], v[156:157] op_sel_hi:[1,0]
	v_pk_mul_f32 v[80:81], v[80:81], v[156:157] op_sel_hi:[1,0]
	v_or_b32_e32 v100, 32, v144
	v_mad_i64_i32 v[100:101], s[26:27], v100, s4, v[148:149]
	v_lshl_add_u64 v[100:101], v[100:101], 0, v[150:151]
	v_pk_mul_f32 v[102:103], v[94:95], v[158:159] op_sel_hi:[1,0]
	v_pk_mul_f32 v[94:95], v[92:93], v[158:159] op_sel_hi:[1,0]
	v_cvt_pk_bf16_f32 v92, v96, v97
	v_cvt_pk_bf16_f32 v93, v98, v99
	v_pk_mul_f32 v[74:75], v[74:75], v[156:157] op_sel_hi:[1,0]
	v_cvt_pk_bf16_f32 v94, v94, v95
	v_cvt_pk_bf16_f32 v95, v102, v103
	global_store_dwordx4 v[100:101], v[92:95], off
	v_pk_mul_f32 v[72:73], v[72:73], v[156:157] op_sel_hi:[1,0]
	v_pk_mul_f32 v[66:67], v[66:67], v[154:155] op_sel_hi:[1,0]
	v_pk_mul_f32 v[92:93], v[86:87], v[158:159] op_sel_hi:[1,0]
	v_pk_mul_f32 v[86:87], v[84:85], v[158:159] op_sel_hi:[1,0]
	v_cvt_pk_bf16_f32 v84, v88, v89
	v_cvt_pk_bf16_f32 v85, v90, v91
	v_pk_mul_f32 v[64:65], v[64:65], v[154:155] op_sel_hi:[1,0]
	v_cvt_pk_bf16_f32 v86, v86, v87
	v_cvt_pk_bf16_f32 v87, v92, v93
	global_store_dwordx4 v[100:101], v[84:87], off offset:256
	v_pk_mul_f32 v[56:57], v[56:57], v[154:155] op_sel_hi:[1,0]
	v_pk_mul_f32 v[58:59], v[58:59], v[154:155] op_sel_hi:[1,0]
	v_or_b32_e32 v84, 48, v144
	v_mad_i64_i32 v[84:85], s[26:27], v84, s4, v[148:149]
	v_lshl_add_u64 v[84:85], v[84:85], 0, v[150:151]
	v_pk_mul_f32 v[86:87], v[78:79], v[156:157] op_sel_hi:[1,0]
	v_pk_mul_f32 v[78:79], v[76:77], v[156:157] op_sel_hi:[1,0]
; __device__ __forceinline__ unsigned cvt_pk_bf16(float lo, float hi) { unsigned r; asm volatile("v_cvt_pk_bf16_f32 %0, %1, %2" : "=v"(r) : "v"(lo), "v"(hi)); return r; }
; #define GAS __attribute__((address_space(1)))
;     __device__ __forceinline__ void operator()(const f32x4 (&acc)[2][2][4][2], const pg8::Unit& u, int wr, int wc, int fr, int fq) const {
;     ...
;             for (int m = 0; m < 4; ++m) { const int row = row0 + ai * 128 + m * 16; const float r = rs[ai * 4 + m]; GAS bf16* rowp = O + (size_t)row * NPROJ + col0;
; #pragma unroll
;                 for (int bj = 0; bj < 2; ++bj) { const f32x4 v0 = acc[ai][bj][m][0] * r, v1 = acc[ai][bj][m][1] * r; v4u w;
;                     w.x = cvt_pk_bf16(v0[0], v0[1]); w.y = cvt_pk_bf16(v0[2], v0[3]); w.z = cvt_pk_bf16(v1[0], v1[1]); w.w = cvt_pk_bf16(v1[2], v1[3]);
;                     *(GAS v4u*)(rowp + bj * 128) = w; } }
	v_cvt_pk_bf16_f32 v76, v80, v81
	v_cvt_pk_bf16_f32 v77, v82, v83
	v_pk_mul_f32 v[52:53], v[52:53], v[152:153] op_sel_hi:[1,0]
	v_cvt_pk_bf16_f32 v78, v78, v79
	v_cvt_pk_bf16_f32 v79, v86, v87
	global_store_dwordx4 v[84:85], v[76:79], off
	v_pk_mul_f32 v[40:41], v[40:41], v[152:153] op_sel_hi:[1,0]
	v_pk_mul_f32 v[42:43], v[42:43], v[152:153] op_sel_hi:[1,0]
	v_pk_mul_f32 v[76:77], v[70:71], v[156:157] op_sel_hi:[1,0]
	v_pk_mul_f32 v[70:71], v[68:69], v[156:157] op_sel_hi:[1,0]
	v_cvt_pk_bf16_f32 v68, v72, v73
	v_cvt_pk_bf16_f32 v69, v74, v75
	v_pk_mul_f32 v[36:37], v[36:37], v[146:147] op_sel_hi:[1,0]
	v_cvt_pk_bf16_f32 v70, v70, v71
	v_cvt_pk_bf16_f32 v71, v76, v77
	global_store_dwordx4 v[84:85], v[68:71], off offset:256
	v_pk_mul_f32 v[24:25], v[24:25], v[146:147] op_sel_hi:[1,0]
	v_pk_mul_f32 v[26:27], v[26:27], v[146:147] op_sel_hi:[1,0]
	v_mad_i64_i32 v[68:69], s[26:27], v145, s4, v[148:149]
	v_lshl_add_u64 v[68:69], v[68:69], 0, v[150:151]
	v_pk_mul_f32 v[70:71], v[62:63], v[154:155] op_sel_hi:[1,0]
	v_pk_mul_f32 v[62:63], v[60:61], v[154:155] op_sel_hi:[1,0]
	v_cvt_pk_bf16_f32 v60, v64, v65
	v_cvt_pk_bf16_f32 v61, v66, v67
	v_pk_mul_f32 v[20:21], v[20:21], v[142:143] op_sel_hi:[1,0]
	v_cvt_pk_bf16_f32 v62, v62, v63
	v_cvt_pk_bf16_f32 v63, v70, v71
	global_store_dwordx4 v[68:69], v[60:63], off
	v_pk_mul_f32 v[10:11], v[10:11], v[142:143] op_sel_hi:[1,0]
	v_pk_mul_f32 v[8:9], v[8:9], v[142:143] op_sel_hi:[1,0]
	v_pk_mul_f32 v[60:61], v[50:51], v[154:155] op_sel_hi:[1,0]
	v_pk_mul_f32 v[50:51], v[48:49], v[154:155] op_sel_hi:[1,0]
	v_cvt_pk_bf16_f32 v48, v56, v57
	v_cvt_pk_bf16_f32 v49, v58, v59
	s_nop 0
	v_cvt_pk_bf16_f32 v50, v50, v51
	v_cvt_pk_bf16_f32 v51, v60, v61
	global_store_dwordx4 v[68:69], v[48:51], off offset:256
	s_nop 1
	v_add_u32_e32 v48, 0x90, v144
	v_mad_i64_i32 v[48:49], s[26:27], v48, s4, v[148:149]
	v_lshl_add_u64 v[48:49], v[48:49], 0, v[150:151]
	v_pk_mul_f32 v[50:51], v[54:55], v[152:153] op_sel_hi:[1,0]
	v_pk_mul_f32 v[54:55], v[46:47], v[152:153] op_sel_hi:[1,0]
	v_pk_mul_f32 v[46:47], v[44:45], v[152:153] op_sel_hi:[1,0]
	v_cvt_pk_bf16_f32 v44, v52, v53
	v_cvt_pk_bf16_f32 v45, v50, v51
	s_nop 0
	v_cvt_pk_bf16_f32 v46, v46, v47
	v_cvt_pk_bf16_f32 v47, v54, v55
	global_store_dwordx4 v[48:49], v[44:47], off
	s_nop 1
	v_pk_mul_f32 v[44:45], v[34:35], v[152:153] op_sel_hi:[1,0]
	v_pk_mul_f32 v[34:35], v[32:33], v[152:153] op_sel_hi:[1,0]
	v_cvt_pk_bf16_f32 v32, v40, v41
	v_cvt_pk_bf16_f32 v33, v42, v43
	s_nop 0
	v_cvt_pk_bf16_f32 v34, v34, v35
	v_cvt_pk_bf16_f32 v35, v44, v45
	global_store_dwordx4 v[48:49], v[32:35], off offset:256
	s_nop 1
	v_add_u32_e32 v32, 0xa0, v144
	v_mad_i64_i32 v[32:33], s[26:27], v32, s4, v[148:149]
	v_lshl_add_u64 v[32:33], v[32:33], 0, v[150:151]
	v_pk_mul_f32 v[34:35], v[38:39], v[146:147] op_sel_hi:[1,0]
	v_pk_mul_f32 v[38:39], v[30:31], v[146:147] op_sel_hi:[1,0]
	v_pk_mul_f32 v[30:31], v[28:29], v[146:147] op_sel_hi:[1,0]
	v_cvt_pk_bf16_f32 v28, v36, v37
	v_cvt_pk_bf16_f32 v29, v34, v35
	s_nop 0
	v_cvt_pk_bf16_f32 v30, v30, v31
	v_cvt_pk_bf16_f32 v31, v38, v39
	global_store_dwordx4 v[32:33], v[28:31], off
	s_nop 1
	v_pk_mul_f32 v[28:29], v[18:19], v[146:147] op_sel_hi:[1,0]
	v_pk_mul_f32 v[18:19], v[16:17], v[146:147] op_sel_hi:[1,0]
	v_cvt_pk_bf16_f32 v16, v24, v25
	v_cvt_pk_bf16_f32 v17, v26, v27
	s_nop 0
	v_cvt_pk_bf16_f32 v18, v18, v19
	v_cvt_pk_bf16_f32 v19, v28, v29
	global_store_dwordx4 v[32:33], v[16:19], off offset:256
	s_nop 1
	v_add_u32_e32 v16, 0xb0, v144
	v_mad_i64_i32 v[16:17], s[26:27], v16, s4, v[148:149]
	v_lshl_add_u64 v[16:17], v[16:17], 0, v[150:151]
	v_pk_mul_f32 v[18:19], v[22:23], v[142:143] op_sel_hi:[1,0]
	v_pk_mul_f32 v[22:23], v[14:15], v[142:143] op_sel_hi:[1,0]
	v_pk_mul_f32 v[14:15], v[12:13], v[142:143] op_sel_hi:[1,0]
	v_cvt_pk_bf16_f32 v12, v20, v21
	v_cvt_pk_bf16_f32 v13, v18, v19
	s_mov_b64 s[26:27], -1
	v_cvt_pk_bf16_f32 v14, v14, v15
	v_cvt_pk_bf16_f32 v15, v22, v23
	global_store_dwordx4 v[16:17], v[12:15], off
	s_nop 1
	v_pk_mul_f32 v[12:13], v[6:7], v[142:143] op_sel_hi:[1,0]
	v_pk_mul_f32 v[6:7], v[4:5], v[142:143] op_sel_hi:[1,0]
	v_cvt_pk_bf16_f32 v4, v8, v9
	v_cvt_pk_bf16_f32 v5, v10, v11
	s_nop 0
	v_cvt_pk_bf16_f32 v6, v6, v7
	v_cvt_pk_bf16_f32 v7, v12, v13
	global_store_dwordx4 v[16:17], v[4:7], off offset:256
	s_cbranch_vccnz .LBB0_82
	s_andn2_b64 vcc, exec, s[0:1]
	s_cbranch_vccnz .LBB0_81
	s_barrier
	s_branch .LBB0_81
